# attention: O^T accumulators + per-lane rescale + LDS-transposed full-line output stores, K/V staging moved ahead of the exp block, s_setprio flips removed
# speedup vs baseline: 1.0030x; 1.0030x over previous
; __device__ __forceinline__ void partialSM(f32x16& p0, f32x16& p1, float& m_reg, float& mn, float& alpha) {
;     ...
;     else { mn = fmaxf(m_reg, pmax); alpha = __builtin_amdgcn_exp2f(m_reg - mn); m_reg = mn; }
; #pragma unroll
;     for (int r = 0; r < 16; ++r) p0[r] = p0[r] - mn;
; #pragma unroll
;     for (int r = 0; r < 16; ++r) p1[r] = p1[r] - mn;
; #pragma unroll
;     for (int r = 0; r < 16; ++r) p0[r] = __builtin_amdgcn_exp2f(p0[r]);
; }
; __device__ __forceinline__ void finishSM(f32x16& p0, f32x16& p1, float alpha, float& l_reg, bf16x8& pa0, bf16x8& pa1, bf16x8& pa2, bf16x8& pa3) {
; #pragma unroll
;     for (int r = 0; r < 16; ++r) p1[r] = __builtin_amdgcn_exp2f(p1[r]);
;     float ps = 0;
; #pragma unroll
;     for (int r = 0; r < 16; ++r) ps += p0[r];
; #pragma unroll
;     for (int r = 0; r < 16; ++r) ps += p1[r];
;     { auto rr = __builtin_amdgcn_permlane32_swap(__float_as_uint(ps), __float_as_uint(ps), false, false);
;       ps = __uint_as_float(rr[0]) + __uint_as_float(rr[1]); }
;     l_reg = l_reg * alpha + ps;
;     ...
;     ATT_PK4(p0, 0, pa0); ATT_PK4(p0, 8, pa1); ATT_PK4(p1, 0, pa2); ATT_PK4(p1, 8, pa3);
.LBB0_826:
	s_add_i32 s92, s11, s86
	s_add_i32 s98, s92, 1
	s_add_i32 s99, s92, 2
	s_waitcnt vmcnt(0)
	s_cmp_ge_i32 s98, s12
	s_cbranch_scc1 .Lstg_a1
	v_add_u32_e32 v238, s82, v188
	v_add_u32_e32 v239, s82, v186
	ds_write_b128 v238, v[146:149] offset:32768
	ds_write_b128 v238, v[150:153] offset:45568
	ds_write_b128 v239, v[154:157] offset:33024
.Lstg_a1:
	s_cmp_ge_i32 s92, s12
	s_cbranch_scc1 .Lstg_a2
	v_add_u32_e32 v238, s59, v182
	v_add_u32_e32 v239, s59, v187
	ds_write_b128 v238, v[138:141]
	ds_write_b128 v239, v[142:145]
.Lstg_a2:
	s_cmp_ge_i32 s99, s12
	s_cbranch_scc1 .Lstg_a3
	s_add_i32 s100, s88, 0xfff80000
	s_add_i32 s101, s89, 0xffffe000
	s_mov_b32 s22, s18
	s_mov_b32 s23, s19
	buffer_load_dwordx4 v[146:149], v193, s[16:19], s100 offen
	buffer_load_dwordx4 v[150:153], v194, s[16:19], s100 offen
	buffer_load_dwordx4 v[154:157], v192, s[20:23], s101 offen
.Lstg_a3:
	s_cmp_ge_i32 s98, s12
	s_cbranch_scc1 .Lstg_a4
	s_add_i32 s100, s88, 0xfff00000
	s_mov_b32 s30, s18
	s_mov_b32 s31, s19
	buffer_load_dwordx4 v[138:141], v193, s[28:31], s100 offen
	buffer_load_dwordx4 v[142:145], v194, s[28:31], s100 offen
.Lstg_a4:
	v_cndmask_b32_e64 v203, v166, v203, s[6:7]
	v_sub_f32_e32 v0, v82, v203
	v_sub_f32_e32 v82, v83, v203
	v_exp_f32_e32 v0, v0
	v_sub_f32_e32 v83, v84, v203
	v_exp_f32_e32 v82, v82
	v_sub_f32_e32 v84, v85, v203
	v_exp_f32_e32 v83, v83
	v_sub_f32_e32 v85, v86, v203
	v_exp_f32_e32 v84, v84
	v_sub_f32_e32 v86, v87, v203
	v_sub_f32_e32 v87, v88, v203
	v_sub_f32_e32 v88, v89, v203
	v_sub_f32_e32 v89, v90, v203
	v_sub_f32_e32 v90, v91, v203
	v_sub_f32_e32 v91, v92, v203
	v_sub_f32_e32 v92, v93, v203
	v_sub_f32_e32 v93, v94, v203
	v_sub_f32_e32 v94, v95, v203
	v_sub_f32_e32 v95, v96, v203
	v_sub_f32_e32 v96, v97, v203
	v_exp_f32_e32 v85, v85
	v_add_f32_e32 v97, 0, v0
	v_exp_f32_e32 v86, v86
	v_add_f32_e32 v97, v82, v97
	v_exp_f32_e32 v87, v87
	v_add_f32_e32 v97, v83, v97
	v_exp_f32_e32 v88, v88
	v_add_f32_e32 v97, v84, v97
	v_exp_f32_e32 v89, v89
	v_add_f32_e32 v97, v85, v97
	v_exp_f32_e32 v90, v90
	v_add_f32_e32 v97, v86, v97
	v_exp_f32_e32 v91, v91
	v_add_f32_e32 v97, v87, v97
	v_exp_f32_e32 v92, v92
	v_add_f32_e32 v97, v88, v97
	v_exp_f32_e32 v93, v93
	v_add_f32_e32 v97, v89, v97
	v_exp_f32_e32 v94, v94
	v_add_f32_e32 v97, v90, v97
	v_exp_f32_e32 v95, v95
	v_add_f32_e32 v97, v91, v97
	v_sub_f32_e32 v66, v66, v203
	v_exp_f32_e32 v96, v96
	v_add_f32_e32 v97, v92, v97
	v_sub_f32_e32 v67, v67, v203
	v_exp_f32_e32 v66, v66
	v_add_f32_e32 v97, v93, v97
	v_sub_f32_e32 v68, v68, v203
	v_exp_f32_e32 v67, v67
	v_add_f32_e32 v97, v94, v97
	v_sub_f32_e32 v69, v69, v203
	v_exp_f32_e32 v68, v68
	v_add_f32_e32 v97, v95, v97
	v_sub_f32_e32 v70, v70, v203
	v_exp_f32_e32 v69, v69
	v_add_f32_e32 v97, v96, v97
	v_sub_f32_e32 v71, v71, v203
	v_exp_f32_e32 v70, v70
	v_add_f32_e32 v97, v66, v97
	v_sub_f32_e32 v72, v72, v203
	v_exp_f32_e32 v71, v71
	v_add_f32_e32 v97, v67, v97
	v_sub_f32_e32 v73, v73, v203
	v_exp_f32_e32 v72, v72
	v_add_f32_e32 v97, v68, v97
	v_sub_f32_e32 v74, v74, v203
	v_exp_f32_e32 v73, v73
	v_add_f32_e32 v97, v69, v97
	v_sub_f32_e32 v75, v75, v203
	v_exp_f32_e32 v74, v74
	v_add_f32_e32 v97, v70, v97
	v_sub_f32_e32 v76, v76, v203
	v_exp_f32_e32 v75, v75
	v_add_f32_e32 v97, v71, v97
	v_sub_f32_e32 v77, v77, v203
	v_exp_f32_e32 v76, v76
	v_add_f32_e32 v97, v72, v97
	v_sub_f32_e32 v78, v78, v203
	v_exp_f32_e32 v77, v77
	v_add_f32_e32 v97, v73, v97
	v_sub_f32_e32 v79, v79, v203
	v_exp_f32_e32 v78, v78
	v_add_f32_e32 v97, v74, v97
	v_sub_f32_e32 v80, v80, v203
	v_exp_f32_e32 v79, v79
	v_add_f32_e32 v97, v75, v97
	v_sub_f32_e32 v81, v81, v203
	v_exp_f32_e32 v80, v80
	v_add_f32_e32 v97, v76, v97
	v_exp_f32_e32 v81, v81
	v_add_f32_e32 v97, v77, v97
	v_add_f32_e32 v97, v78, v97
	v_add_f32_e32 v97, v79, v97
	v_add_f32_e32 v97, v80, v97
	v_add_f32_e32 v204, v81, v97
	v_cvt_pk_bf16_f32 v166, v0, v82
	v_cvt_pk_bf16_f32 v167, v83, v84
	v_cvt_pk_bf16_f32 v168, v85, v86
	v_cvt_pk_bf16_f32 v169, v87, v88
	v_cvt_pk_bf16_f32 v170, v89, v90
	v_cvt_pk_bf16_f32 v171, v91, v92
	v_cvt_pk_bf16_f32 v172, v93, v94
	v_cvt_pk_bf16_f32 v173, v95, v96
	v_cvt_pk_bf16_f32 v174, v66, v67
	v_cvt_pk_bf16_f32 v175, v68, v69
	v_cvt_pk_bf16_f32 v176, v70, v71
	v_cvt_pk_bf16_f32 v177, v72, v73
	v_cvt_pk_bf16_f32 v178, v74, v75
	v_cvt_pk_bf16_f32 v179, v76, v77
	v_cvt_pk_bf16_f32 v180, v78, v79
	v_cvt_pk_bf16_f32 v181, v80, v81
	v_mov_b32_e32 v205, v204
	s_nop 1
	v_permlane32_swap_b32_e32 v204, v205
	v_permlane32_swap_b32_e32 v166, v168
	v_permlane32_swap_b32_e32 v167, v169
	v_permlane32_swap_b32_e32 v170, v172
	v_permlane32_swap_b32_e32 v171, v173
	v_permlane32_swap_b32_e32 v174, v176
	v_permlane32_swap_b32_e32 v175, v177
	v_permlane32_swap_b32_e32 v178, v180
	v_permlane32_swap_b32_e32 v179, v181
	s_waitcnt lgkmcnt(0)
	s_barrier
; #define ATT_SBAR() __builtin_amdgcn_sched_barrier(0)
; #define QP_LD(d, s) do { ka[s] = *reinterpret_cast<const bf16x8*>(r0 + (d) * 32); kb[s] = *reinterpret_cast<const bf16x8*>(r1 + (d) * 32); } while (0)
; #define ATT_TRB(vb, off) __builtin_amdgcn_ds_read_tr16_b64_v4i16((LAS s16x4*)(unsigned)((vb) + (off)))
; #define QP_LD(d, s) do { ka[s] = *reinterpret_cast<const bf16x8*>(r0 + (d) * 32); kb[s] = *reinterpret_cast<const bf16x8*>(r1 + (d) * 32); } while (0)
; template <int DK> __device__ __forceinline__ void qkt_pipe_pv(f32x16& p0, f32x16& p1, const char* Ks, const bf16x8* qr, int r32, int hi, int vb, s16x4 (&F)[8]) {
;     constexpr int ND = DK / 16, KR = DK * 2 + 16;
;     const char* r0 = Ks + ATT_KSWZ(r32, hi * 16, KR); const char* r1 = Ks + ATT_KSWZ(32 + r32, hi * 16, KR);
;     bf16x8 ka[3], kb[3];
;     ...
;     QP_LD(0, 0); QP_LD(1, 1); QP_LD(2, 2); ATT_SBAR();
;     p0 = f32x16{}; p1 = f32x16{};
;     __builtin_amdgcn_s_setprio(1);
; #pragma unroll
;     for (int d0 = 0; d0 < ND; ++d0) {
;         p0 = __builtin_amdgcn_mfma_f32_32x32x16_bf16(ka[d0 % 3], qr[d0], p0, 0, 0, 0);
;         p1 = __builtin_amdgcn_mfma_f32_32x32x16_bf16(kb[d0 % 3], qr[d0], p1, 0, 0, 0);
;         if (d0 + 3 < ND) QP_LD(d0 + 3, d0 % 3);
;         if (d0 == ND - 3) { F[0] = ATT_TRB(vb, v_rd_off(0, 0, 0)); F[1] = ATT_TRB(vb, v_rd_off(0, 0, 1)); F[2] = ATT_TRB(vb, v_rd_off(0, 1, 0)); F[3] = ATT_TRB(vb, v_rd_off(0, 1, 1)); }
;         if (d0 == ND - 2) { F[4] = ATT_TRB(vb, v_rd_off(0, 2, 0)); F[5] = ATT_TRB(vb, v_rd_off(0, 2, 1)); F[6] = ATT_TRB(vb, v_rd_off(0, 3, 0)); F[7] = ATT_TRB(vb, v_rd_off(0, 3, 1)); }
;         ATT_SBAR(); }
;     __builtin_amdgcn_s_setprio(0);
;     ...
; }
; __device__ __forceinline__ void pv_d0_pre(f32x16* o, int vb, bf16x8 pa0, bf16x8 pa1, bf16x8 pa2, bf16x8 pa3, s16x4 (&F)[8]) {
;     s16x4 G[8];
;     ...
;     PVB_RD(1, G); ATT_SBAR(); PVB_MM(0, F); ATT_SBAR();
;     PVB_RD(2, F); ATT_SBAR(); PVB_MM(1, G); ATT_SBAR();
;     PVB_RD(3, G); ATT_SBAR(); PVB_MM(2, F); ATT_SBAR();
;     PVB_MM(3, G);
;     ...
; }
	ds_read_b128 v[66:69], v195 offset:58368
	ds_read_b128 v[206:209], v195 offset:58400
	ds_read_b128 v[70:73], v198 offset:12800
	ds_read_b128 v[210:213], v195 offset:58432
	ds_read_b128 v[214:217], v198 offset:12832
	ds_read_b128 v[218:221], v198 offset:12864
	s_waitcnt lgkmcnt(5)
	v_mfma_f32_32x32x16_bf16 v[82:97], v[66:69], v[98:101], 0
	ds_read_b128 v[222:225], v195 offset:58464
	ds_read_b128 v[226:229], v198 offset:12896
	s_waitcnt lgkmcnt(5)
	v_mfma_f32_32x32x16_bf16 v[66:81], v[70:73], v[98:101], 0
	v_mfma_f32_32x32x16_bf16 v[82:97], v[206:209], v[102:105], v[82:97]
	ds_read_b128 v[206:209], v195 offset:58496
	ds_read_b128 v[230:233], v198 offset:12928
	s_waitcnt lgkmcnt(5)
	v_mfma_f32_32x32x16_bf16 v[66:81], v[214:217], v[102:105], v[66:81]
	v_mfma_f32_32x32x16_bf16 v[82:97], v[210:213], v[106:109], v[82:97]
	ds_read_b128 v[210:213], v195 offset:58528
	ds_read_b128 v[214:217], v198 offset:12960
	s_waitcnt lgkmcnt(6)
	v_mfma_f32_32x32x16_bf16 v[66:81], v[218:221], v[106:109], v[66:81]
	s_waitcnt lgkmcnt(5)
	v_mfma_f32_32x32x16_bf16 v[82:97], v[222:225], v[110:113], v[82:97]
	ds_read_b128 v[218:221], v195 offset:58560
	ds_read_b128 v[222:225], v198 offset:12992
	s_waitcnt lgkmcnt(6)
	v_mfma_f32_32x32x16_bf16 v[66:81], v[226:229], v[110:113], v[66:81]
	s_waitcnt lgkmcnt(5)
	v_mfma_f32_32x32x16_bf16 v[82:97], v[206:209], v[114:117], v[82:97]
	ds_read_b128 v[206:209], v195 offset:58592
	ds_read_b128 v[226:229], v198 offset:13024
	s_waitcnt lgkmcnt(6)
	v_mfma_f32_32x32x16_bf16 v[66:81], v[230:233], v[114:117], v[66:81]
	s_waitcnt lgkmcnt(5)
	v_mfma_f32_32x32x16_bf16 v[82:97], v[210:213], v[118:121], v[82:97]
	ds_read_b128 v[210:213], v195 offset:58624
	ds_read_b128 v[230:233], v198 offset:13056
	s_waitcnt lgkmcnt(6)
	v_mfma_f32_32x32x16_bf16 v[66:81], v[214:217], v[118:121], v[66:81]
	s_waitcnt lgkmcnt(5)
	v_mfma_f32_32x32x16_bf16 v[82:97], v[218:221], v[122:125], v[82:97]
	ds_read_b128 v[214:217], v195 offset:58656
	ds_read_b128 v[218:221], v198 offset:13088
	s_waitcnt lgkmcnt(6)
	v_mfma_f32_32x32x16_bf16 v[66:81], v[222:225], v[122:125], v[66:81]
	s_waitcnt lgkmcnt(5)
	v_mfma_f32_32x32x16_bf16 v[82:97], v[206:209], v[126:129], v[82:97]
	ds_read_b128 v[206:209], v195 offset:58688
	ds_read_b128 v[222:225], v198 offset:13120
	s_waitcnt lgkmcnt(6)
	v_mfma_f32_32x32x16_bf16 v[66:81], v[226:229], v[126:129], v[66:81]
	s_waitcnt lgkmcnt(5)
	v_mfma_f32_32x32x16_bf16 v[82:97], v[210:213], v[130:133], v[82:97]
	ds_read_b128 v[210:213], v195 offset:58720
	ds_read_b128 v[226:229], v198 offset:13152
	s_waitcnt lgkmcnt(6)
	v_mfma_f32_32x32x16_bf16 v[66:81], v[230:233], v[130:133], v[66:81]
	s_waitcnt lgkmcnt(5)
	v_mfma_f32_32x32x16_bf16 v[82:97], v[214:217], v[158:161], v[82:97]
	ds_read_b64_tr_b16 v[214:215], v197
	ds_read_b64_tr_b16 v[216:217], v197 offset:2048
	ds_read_b64_tr_b16 v[230:231], v197 offset:4096
	ds_read_b64_tr_b16 v[232:233], v197 offset:6144
	s_waitcnt lgkmcnt(8)
	v_mfma_f32_32x32x16_bf16 v[66:81], v[218:221], v[158:161], v[66:81]
	s_waitcnt lgkmcnt(7)
	v_mfma_f32_32x32x16_bf16 v[82:97], v[206:209], v[134:137], v[82:97]
	ds_read_b64_tr_b16 v[206:207], v197 offset:8192
	ds_read_b64_tr_b16 v[208:209], v197 offset:10240
	ds_read_b64_tr_b16 v[218:219], v197 offset:12288
	ds_read_b64_tr_b16 v[220:221], v197 offset:14336
	s_waitcnt lgkmcnt(10)
	v_mfma_f32_32x32x16_bf16 v[66:81], v[222:225], v[134:137], v[66:81]
	s_waitcnt lgkmcnt(9)
	v_mfma_f32_32x32x16_bf16 v[82:97], v[210:213], v[162:165], v[82:97]
	s_waitcnt lgkmcnt(8)
	v_mfma_f32_32x32x16_bf16 v[66:81], v[226:229], v[162:165], v[66:81]
	ds_read_b64_tr_b16 v[210:211], v197 offset:512
	ds_read_b64_tr_b16 v[212:213], v197 offset:2560
	ds_read_b64_tr_b16 v[222:223], v197 offset:4608
	ds_read_b64_tr_b16 v[224:225], v197 offset:6656
	ds_read_b64_tr_b16 v[226:227], v197 offset:8704
	ds_read_b64_tr_b16 v[228:229], v197 offset:10752
	ds_read_b64_tr_b16 v[234:235], v197 offset:12800
	ds_read_b64_tr_b16 v[236:237], v197 offset:14848
	s_waitcnt lgkmcnt(14)
	v_mfma_f32_32x32x16_bf16 v[18:33], v[214:217], v[166:169], v[18:33]
	s_waitcnt lgkmcnt(12)
	v_mfma_f32_32x32x16_bf16 v[18:33], v[230:233], v[170:173], v[18:33]
	s_waitcnt lgkmcnt(10)
	v_mfma_f32_32x32x16_bf16 v[18:33], v[206:209], v[174:177], v[18:33]
	s_waitcnt lgkmcnt(8)
	v_mfma_f32_32x32x16_bf16 v[18:33], v[218:221], v[178:181], v[18:33]
	ds_read_b64_tr_b16 v[206:207], v197 offset:1024
	ds_read_b64_tr_b16 v[208:209], v197 offset:3072
	ds_read_b64_tr_b16 v[214:215], v197 offset:5120
	ds_read_b64_tr_b16 v[216:217], v197 offset:7168
	ds_read_b64_tr_b16 v[218:219], v197 offset:9216
	ds_read_b64_tr_b16 v[220:221], v197 offset:11264
	ds_read_b64_tr_b16 v[230:231], v197 offset:13312
	ds_read_b64_tr_b16 v[232:233], v197 offset:15360
	s_waitcnt lgkmcnt(14)
	v_mfma_f32_32x32x16_bf16 v[34:49], v[210:213], v[166:169], v[34:49]
	s_waitcnt lgkmcnt(12)
	v_mfma_f32_32x32x16_bf16 v[34:49], v[222:225], v[170:173], v[34:49]
	s_waitcnt lgkmcnt(10)
	v_mfma_f32_32x32x16_bf16 v[34:49], v[226:229], v[174:177], v[34:49]
	s_waitcnt lgkmcnt(8)
	v_mfma_f32_32x32x16_bf16 v[34:49], v[234:237], v[178:181], v[34:49]
	ds_read_b64_tr_b16 v[210:211], v197 offset:1536
	ds_read_b64_tr_b16 v[212:213], v197 offset:3584
	ds_read_b64_tr_b16 v[222:223], v197 offset:5632
	ds_read_b64_tr_b16 v[224:225], v197 offset:7680
	ds_read_b64_tr_b16 v[226:227], v197 offset:9728
	ds_read_b64_tr_b16 v[228:229], v197 offset:11776
	ds_read_b64_tr_b16 v[234:235], v197 offset:13824
	ds_read_b64_tr_b16 v[236:237], v197 offset:15872
	s_waitcnt lgkmcnt(14)
	v_mfma_f32_32x32x16_bf16 v[50:65], v[206:209], v[166:169], v[50:65]
	s_waitcnt lgkmcnt(12)
	v_mfma_f32_32x32x16_bf16 v[50:65], v[214:217], v[170:173], v[50:65]
	s_waitcnt lgkmcnt(10)
	v_mfma_f32_32x32x16_bf16 v[50:65], v[218:221], v[174:177], v[50:65]
	s_waitcnt lgkmcnt(8)
	v_mfma_f32_32x32x16_bf16 v[50:65], v[230:233], v[178:181], v[50:65]
	s_waitcnt lgkmcnt(6)
	v_mfma_f32_32x32x16_bf16 v[2:17], v[210:213], v[166:169], v[2:17]
	s_waitcnt lgkmcnt(4)
	v_mfma_f32_32x32x16_bf16 v[2:17], v[222:225], v[170:173], v[2:17]
	s_waitcnt lgkmcnt(2)
	v_mfma_f32_32x32x16_bf16 v[2:17], v[226:229], v[174:177], v[2:17]
	s_waitcnt lgkmcnt(0)
	v_mfma_f32_32x32x16_bf16 v[2:17], v[234:237], v[178:181], v[2:17]
	s_waitcnt lgkmcnt(0)
	s_barrier
; __device__ __forceinline__ int crow(int r, int hi) { return (r & 3) + 8 * (r >> 2) + 4 * hi; }
; __device__ __forceinline__ void cmask(f32x16& p0, f32x16& p1, int t, int qrel, int hi) {
;     const float ninf = -__builtin_inff();
; #pragma unroll
;     for (int r = 0; r < 16; ++r) { const int k0 = 64 * t + crow(r, hi); if (k0 > qrel) p0[r] = ninf; if (k0 + 32 > qrel) p1[r] = ninf; }
; }
	s_add_i32 s8, s8, 1
	s_cmp_lt_i32 s8, 0
	s_cbranch_scc1 .LBB0_837
	s_cmp_le_i32 s58, s83
	s_cbranch_scc1 .LBB0_837
	v_add_u32_e32 v0, s58, v196
	v_subrev_u32_e32 v167, 31, v0
	v_subrev_u32_e32 v166, 63, v0
	v_cmp_le_i32_e32 vcc, v167, v200
	s_nop 1
	v_cndmask_b32_e32 v66, v190, v66, vcc
	v_cmp_lt_i32_e32 vcc, v166, v200
	s_nop 1
	v_cndmask_b32_e32 v83, v190, v83, vcc
	v_cmp_le_i32_e32 vcc, v166, v200
	v_subrev_u32_e32 v166, 30, v0
	s_nop 0
	v_cndmask_b32_e32 v82, v190, v82, vcc
	v_cmp_le_i32_e32 vcc, v166, v200
	v_subrev_u32_e32 v166, 61, v0
	s_nop 0
	v_cndmask_b32_e32 v67, v190, v67, vcc
	v_cmp_le_i32_e32 vcc, v166, v200
	v_subrev_u32_e32 v166, 29, v0
	s_nop 0
	v_cndmask_b32_e32 v84, v190, v84, vcc
	v_cmp_le_i32_e32 vcc, v166, v200
	v_subrev_u32_e32 v166, 60, v0
	s_nop 0
	v_cndmask_b32_e32 v68, v190, v68, vcc
	v_cmp_le_i32_e32 vcc, v166, v200
	v_subrev_u32_e32 v166, 28, v0
	s_nop 0
	v_cndmask_b32_e32 v85, v190, v85, vcc
	v_cmp_le_i32_e32 vcc, v166, v200
	v_subrev_u32_e32 v166, 55, v0
	s_nop 0
	v_cndmask_b32_e32 v69, v190, v69, vcc
	v_cmp_le_i32_e32 vcc, v166, v200
	v_subrev_u32_e32 v166, 23, v0
	s_nop 0
	v_cndmask_b32_e32 v86, v190, v86, vcc
	v_cmp_le_i32_e32 vcc, v166, v200
	v_subrev_u32_e32 v166, 54, v0
	s_nop 0
	v_cndmask_b32_e32 v70, v190, v70, vcc
	v_cmp_le_i32_e32 vcc, v166, v200
	v_subrev_u32_e32 v166, 22, v0
	s_nop 0
	v_cndmask_b32_e32 v87, v190, v87, vcc
	v_cmp_le_i32_e32 vcc, v166, v200
	v_subrev_u32_e32 v166, 53, v0
	s_nop 0
	v_cndmask_b32_e32 v71, v190, v71, vcc
	v_cmp_le_i32_e32 vcc, v166, v200
	v_subrev_u32_e32 v166, 21, v0
	s_nop 0
	v_cndmask_b32_e32 v88, v190, v88, vcc
	v_cmp_le_i32_e32 vcc, v166, v200
	v_subrev_u32_e32 v166, 52, v0
	s_nop 0
	v_cndmask_b32_e32 v72, v190, v72, vcc
	v_cmp_le_i32_e32 vcc, v166, v200
	v_subrev_u32_e32 v166, 20, v0
	s_nop 0
	v_cndmask_b32_e32 v89, v190, v89, vcc
	v_cmp_le_i32_e32 vcc, v166, v200
	v_subrev_u32_e32 v166, 47, v0
	s_nop 0
	v_cndmask_b32_e32 v73, v190, v73, vcc
	v_cmp_le_i32_e32 vcc, v166, v200
	v_add_u32_e32 v166, -15, v0
	s_nop 0
	v_cndmask_b32_e32 v90, v190, v90, vcc
	v_cmp_le_i32_e32 vcc, v166, v200
	v_subrev_u32_e32 v166, 46, v0
	s_nop 0
	v_cndmask_b32_e32 v74, v190, v74, vcc
	v_cmp_le_i32_e32 vcc, v166, v200
	v_add_u32_e32 v166, -14, v0
	s_nop 0
	v_cndmask_b32_e32 v91, v190, v91, vcc
	v_cmp_le_i32_e32 vcc, v166, v200
	v_subrev_u32_e32 v166, 45, v0
	s_nop 0
	v_cndmask_b32_e32 v75, v190, v75, vcc
	v_cmp_le_i32_e32 vcc, v166, v200
	v_add_u32_e32 v166, -13, v0
	s_nop 0
	v_cndmask_b32_e32 v92, v190, v92, vcc
	v_cmp_le_i32_e32 vcc, v166, v200
	v_subrev_u32_e32 v166, 44, v0
	s_nop 0
	v_cndmask_b32_e32 v76, v190, v76, vcc
	v_cmp_le_i32_e32 vcc, v166, v200
	v_add_u32_e32 v166, -12, v0
	s_nop 0
	v_cndmask_b32_e32 v93, v190, v93, vcc
	v_cmp_le_i32_e32 vcc, v166, v200
	v_subrev_u32_e32 v166, 39, v0
	s_nop 0
	v_cndmask_b32_e32 v77, v190, v77, vcc
	v_cmp_le_i32_e32 vcc, v166, v200
	v_add_u32_e32 v166, -7, v0
	s_nop 0
	v_cndmask_b32_e32 v94, v190, v94, vcc
	v_cmp_le_i32_e32 vcc, v166, v200
	v_subrev_u32_e32 v166, 38, v0
	s_nop 0
	v_cndmask_b32_e32 v78, v190, v78, vcc
	v_cmp_le_i32_e32 vcc, v166, v200
	v_add_u32_e32 v166, -6, v0
	s_nop 0
	v_cndmask_b32_e32 v95, v190, v95, vcc
	v_cmp_le_i32_e32 vcc, v166, v200
	v_subrev_u32_e32 v166, 37, v0
	s_nop 0
	v_cndmask_b32_e32 v79, v190, v79, vcc
	v_cmp_le_i32_e32 vcc, v166, v200
	v_add_u32_e32 v166, -5, v0
	s_nop 0
	v_cndmask_b32_e32 v96, v190, v96, vcc
	v_cmp_le_i32_e32 vcc, v166, v200
	v_subrev_u32_e32 v166, 36, v0
	v_add_u32_e32 v0, -4, v0
	v_cndmask_b32_e32 v80, v190, v80, vcc
	v_cmp_le_i32_e32 vcc, v166, v200
	s_nop 1
	v_cndmask_b32_e32 v97, v190, v97, vcc
	v_cmp_le_i32_e32 vcc, v0, v200
	s_nop 1
	v_cndmask_b32_e32 v81, v190, v81, vcc

; __device__ __forceinline__ void partialSM(f32x16& p0, f32x16& p1, float& m_reg, float& mn, float& alpha) {
;     ...
; #pragma unroll
;     for (int r = 0; r < 16; ++r) p0[r] = p0[r] - mn;
; #pragma unroll
;     for (int r = 0; r < 16; ++r) p1[r] = p1[r] - mn;
; #pragma unroll
;     for (int r = 0; r < 16; ++r) p0[r] = __builtin_amdgcn_exp2f(p0[r]);
; }
; __device__ __forceinline__ void finishSM(f32x16& p0, f32x16& p1, float alpha, float& l_reg, bf16x8& pa0, bf16x8& pa1, bf16x8& pa2, bf16x8& pa3) {
; #pragma unroll
;     for (int r = 0; r < 16; ++r) p1[r] = __builtin_amdgcn_exp2f(p1[r]);
;     float ps = 0;
; #pragma unroll
;     for (int r = 0; r < 16; ++r) ps += p0[r];
; #pragma unroll
;     for (int r = 0; r < 16; ++r) ps += p1[r];
;     { auto rr = __builtin_amdgcn_permlane32_swap(__float_as_uint(ps), __float_as_uint(ps), false, false);
;       ps = __uint_as_float(rr[0]) + __uint_as_float(rr[1]); }
;     l_reg = l_reg * alpha + ps;
;     ...
;     ATT_PK4(p0, 0, pa0); ATT_PK4(p0, 8, pa1); ATT_PK4(p1, 0, pa2); ATT_PK4(p1, 8, pa3);
.LBB0_841:
	s_add_i32 s92, s11, s86
	s_add_i32 s98, s92, 1
	s_add_i32 s99, s92, 2
	s_add_i32 s100, s92, 3
	s_waitcnt vmcnt(0)
	s_cmp_ge_i32 s99, s12
	s_cbranch_scc1 .Lstg_b1
	v_add_u32_e32 v238, s87, v188
	v_add_u32_e32 v239, s87, v186
	ds_write_b128 v238, v[146:149] offset:32768
	ds_write_b128 v238, v[150:153] offset:45568
	ds_write_b128 v239, v[154:157] offset:33024
.Lstg_b1:
	s_cmp_ge_i32 s98, s12
	s_cbranch_scc1 .Lstg_b2
	s_and_b32 s101, s91, 0x4000
	v_add_u32_e32 v238, s101, v182
	v_add_u32_e32 v239, s101, v187
	ds_write_b128 v238, v[138:141]
	ds_write_b128 v239, v[142:145]
.Lstg_b2:
	s_cmp_ge_i32 s100, s12
	s_cbranch_scc1 .Lstg_b3
	s_mov_b32 s22, s18
	s_mov_b32 s23, s19
	buffer_load_dwordx4 v[146:149], v193, s[16:19], s88 offen
	buffer_load_dwordx4 v[150:153], v194, s[16:19], s88 offen
	buffer_load_dwordx4 v[154:157], v192, s[20:23], s89 offen
.Lstg_b3:
	s_cmp_ge_i32 s99, s12
	s_cbranch_scc1 .Lstg_b4
	s_add_i32 s101, s88, 0xfff80000
	s_mov_b32 s30, s18
	s_mov_b32 s31, s19
	buffer_load_dwordx4 v[138:141], v193, s[28:31], s101 offen
	buffer_load_dwordx4 v[142:145], v194, s[28:31], s101 offen
.Lstg_b4:
	v_cndmask_b32_e64 v203, v166, v203, s[8:9]
	v_sub_f32_e32 v0, v82, v203
	v_sub_f32_e32 v82, v83, v203
	v_exp_f32_e32 v0, v0
	v_sub_f32_e32 v83, v84, v203
	v_exp_f32_e32 v82, v82
	v_sub_f32_e32 v84, v85, v203
	v_exp_f32_e32 v83, v83
	v_sub_f32_e32 v85, v86, v203
	v_sub_f32_e32 v66, v66, v203
	v_exp_f32_e32 v84, v84
	v_sub_f32_e32 v86, v87, v203
	v_sub_f32_e32 v87, v88, v203
	v_sub_f32_e32 v88, v89, v203
	v_sub_f32_e32 v89, v90, v203
	v_sub_f32_e32 v90, v91, v203
	v_sub_f32_e32 v91, v92, v203
	v_sub_f32_e32 v92, v93, v203
	v_sub_f32_e32 v93, v94, v203
	v_sub_f32_e32 v94, v95, v203
	v_sub_f32_e32 v95, v96, v203
	v_sub_f32_e32 v96, v97, v203
	v_exp_f32_e32 v85, v85
	v_exp_f32_e32 v97, v66
	v_add_f32_e32 v66, 0, v0
	v_exp_f32_e32 v86, v86
	v_add_f32_e32 v66, v82, v66
	v_exp_f32_e32 v87, v87
	v_add_f32_e32 v66, v83, v66
	v_exp_f32_e32 v88, v88
	v_add_f32_e32 v66, v84, v66
	v_exp_f32_e32 v89, v89
	v_add_f32_e32 v66, v85, v66
	v_exp_f32_e32 v90, v90
	v_add_f32_e32 v66, v86, v66
	v_exp_f32_e32 v91, v91
	v_add_f32_e32 v66, v87, v66
	v_exp_f32_e32 v92, v92
	v_add_f32_e32 v66, v88, v66
	v_exp_f32_e32 v93, v93
	v_add_f32_e32 v66, v89, v66
	v_exp_f32_e32 v94, v94
	v_add_f32_e32 v66, v90, v66
	v_exp_f32_e32 v95, v95
	v_add_f32_e32 v66, v91, v66
	v_exp_f32_e32 v96, v96
	v_add_f32_e32 v66, v92, v66
	v_sub_f32_e32 v67, v67, v203
	v_add_f32_e32 v66, v93, v66
	v_sub_f32_e32 v68, v68, v203
	v_exp_f32_e32 v174, v67
	v_add_f32_e32 v66, v94, v66
	v_sub_f32_e32 v69, v69, v203
	v_exp_f32_e32 v68, v68
	v_add_f32_e32 v66, v95, v66
	v_sub_f32_e32 v70, v70, v203
	v_exp_f32_e32 v69, v69
	v_add_f32_e32 v66, v96, v66
	v_sub_f32_e32 v71, v71, v203
	v_exp_f32_e32 v70, v70
	v_add_f32_e32 v66, v97, v66
	v_sub_f32_e32 v72, v72, v203
	v_exp_f32_e32 v71, v71
	v_add_f32_e32 v66, v174, v66
	v_sub_f32_e32 v73, v73, v203
	v_exp_f32_e32 v72, v72
	v_add_f32_e32 v66, v68, v66
	v_sub_f32_e32 v74, v74, v203
	v_exp_f32_e32 v73, v73
	v_add_f32_e32 v66, v69, v66
	v_sub_f32_e32 v75, v75, v203
	v_exp_f32_e32 v74, v74
	v_add_f32_e32 v66, v70, v66
	v_sub_f32_e32 v76, v76, v203
	v_exp_f32_e32 v75, v75
	v_add_f32_e32 v66, v71, v66
	v_sub_f32_e32 v77, v77, v203
	v_exp_f32_e32 v76, v76
	v_add_f32_e32 v66, v72, v66
	v_sub_f32_e32 v78, v78, v203
	v_exp_f32_e32 v77, v77
	v_add_f32_e32 v66, v73, v66
	v_sub_f32_e32 v79, v79, v203
	v_exp_f32_e32 v78, v78
	v_add_f32_e32 v66, v74, v66
	v_sub_f32_e32 v80, v80, v203
	v_exp_f32_e32 v79, v79
	v_add_f32_e32 v66, v75, v66
	v_sub_f32_e32 v81, v81, v203
	v_exp_f32_e32 v80, v80
	v_add_f32_e32 v66, v76, v66
	v_exp_f32_e32 v81, v81
	v_add_f32_e32 v66, v77, v66
	v_add_f32_e32 v66, v78, v66
	v_add_f32_e32 v66, v79, v66
	v_add_f32_e32 v66, v80, v66
	v_add_f32_e32 v66, v81, v66
	v_cvt_pk_bf16_f32 v166, v0, v82
	v_cvt_pk_bf16_f32 v167, v83, v84
	v_cvt_pk_bf16_f32 v168, v85, v86
	v_cvt_pk_bf16_f32 v169, v87, v88
	v_cvt_pk_bf16_f32 v170, v89, v90
	v_cvt_pk_bf16_f32 v171, v91, v92
	v_cvt_pk_bf16_f32 v172, v93, v94
	v_cvt_pk_bf16_f32 v173, v95, v96
	v_cvt_pk_bf16_f32 v174, v97, v174
	v_cvt_pk_bf16_f32 v175, v68, v69
	v_cvt_pk_bf16_f32 v176, v70, v71
	v_cvt_pk_bf16_f32 v177, v72, v73
	v_cvt_pk_bf16_f32 v178, v74, v75
	v_cvt_pk_bf16_f32 v179, v76, v77
	v_cvt_pk_bf16_f32 v180, v78, v79
	v_cvt_pk_bf16_f32 v181, v80, v81
	v_mov_b32_e32 v67, v66
	s_nop 1
	v_permlane32_swap_b32_e32 v66, v67
	v_permlane32_swap_b32_e32 v166, v168
	v_permlane32_swap_b32_e32 v167, v169
	v_permlane32_swap_b32_e32 v170, v172
	v_permlane32_swap_b32_e32 v171, v173
	v_permlane32_swap_b32_e32 v174, v176
	v_permlane32_swap_b32_e32 v175, v177
	v_permlane32_swap_b32_e32 v178, v180
	v_permlane32_swap_b32_e32 v179, v181
	s_branch .LBB0_818
